# attention fast path: next-tile softmax VALU interleaved between the P.V MFMAs (rare rescale falls back to original order)
# speedup vs baseline: 1.0057x; 1.0057x over previous
.Li0_entry:
	s_waitcnt lgkmcnt(0)
	v_max_f32_e32 v72, v166, v166
	v_max_f32_e32 v73, v164, v164
	v_max_f32_e32 v72, v73, v72
	v_sub_f32_e32 v73, v72, v165
	v_mul_f32_e32 v73, 0x3db504f3, v73
	v_cmp_ge_f32_e32 vcc, s88, v73
	s_cmp_eq_u64 vcc, exec
	s_cbranch_scc0 .LBB0_737
	v_add_u32_e32 v167, s79, v147
	ds_read_b128 v[64:67], v167
	v_add_u32_e32 v188, s79, v149
	ds_read_b128 v[180:183], v188
	v_add_u32_e32 v189, s79, v151
	v_add_u32_e32 v190, s79, v153
	s_waitcnt lgkmcnt(0)
	v_mfma_f32_32x32x16_bf16 v[64:79], v[64:67], v[80:83], 0
	v_mfma_f32_32x32x16_bf16 v[64:79], v[180:183], v[84:87], v[64:79]
	ds_read_b128 v[180:183], v189
	s_waitcnt lgkmcnt(0)
	v_mfma_f32_32x32x16_bf16 v[64:79], v[180:183], v[88:91], v[64:79]
	ds_read_b128 v[180:183], v190
	s_waitcnt lgkmcnt(0)
	v_mfma_f32_32x32x16_bf16 v[64:79], v[180:183], v[92:95], v[64:79]
	ds_read_b128 v[180:183], v167 offset:128
	s_waitcnt lgkmcnt(0)
	v_mfma_f32_32x32x16_bf16 v[64:79], v[180:183], v[96:99], v[64:79]
	ds_read_b128 v[180:183], v188 offset:128
	s_waitcnt lgkmcnt(0)
	v_mfma_f32_32x32x16_bf16 v[64:79], v[180:183], v[100:103], v[64:79]
	ds_read_b128 v[180:183], v189 offset:128
	s_waitcnt lgkmcnt(0)
	v_mfma_f32_32x32x16_bf16 v[64:79], v[180:183], v[104:107], v[64:79]
	ds_read_b128 v[180:183], v190 offset:128
	s_waitcnt lgkmcnt(0)
	v_mfma_f32_32x32x16_bf16 v[64:79], v[180:183], v[108:111], v[64:79]
	v_cndmask_b32_e64 v173, v113, v121, s[2:3]
	v_cndmask_b32_e64 v172, v112, v120, s[2:3]
	v_cndmask_b32_e64 v177, v121, v113, s[2:3]
	v_cndmask_b32_e64 v176, v120, v112, s[2:3]
	v_cndmask_b32_e64 v171, v119, v127, s[2:3]
	v_cndmask_b32_e64 v170, v118, v126, s[2:3]
	v_cndmask_b32_e64 v169, v117, v125, s[2:3]
	v_cndmask_b32_e64 v168, v116, v124, s[2:3]
	v_cndmask_b32_e64 v175, v115, v123, s[2:3]
	v_cndmask_b32_e64 v174, v114, v122, s[2:3]
	v_cndmask_b32_e64 v127, v127, v119, s[2:3]
	v_cndmask_b32_e64 v126, v126, v118, s[2:3]
	v_cndmask_b32_e64 v125, v125, v117, s[2:3]
	v_cndmask_b32_e64 v124, v124, v116, s[2:3]
	v_cndmask_b32_e64 v179, v123, v115, s[2:3]
	v_cndmask_b32_e64 v178, v122, v114, s[2:3]
	v_mov_b32_e32 v166, v165
	s_sub_i32 s52, s83, 64
	s_cmp_le_i32 s52, s25
	s_cbranch_scc1 .Li0_sm
	v_add_u32_e32 v112, 0x5b, v162
	v_cmp_gt_u32_e32 vcc, s86, v112
	v_add_u32_e32 v112, s83, v163
	v_add_u32_e32 v112, 0xffffffa1, v112
	v_cndmask_b32_e32 v64, v141, v64, vcc
	v_cmp_lt_u32_e32 vcc, s87, v112
	v_add_u32_e32 v112, 0x59, v162
	s_nop 0
	v_cndmask_b32_e32 v65, v141, v65, vcc
	v_cmp_gt_u32_e32 vcc, s86, v112
	v_add_u32_e32 v112, 0x58, v162
	s_nop 0
	v_cndmask_b32_e32 v66, v141, v66, vcc
	v_cmp_gt_u32_e32 vcc, s86, v112
	v_add_u32_e32 v112, 0x53, v162
	s_nop 0
	v_cndmask_b32_e32 v67, v141, v67, vcc
	v_cmp_gt_u32_e32 vcc, s86, v112
	v_add_u32_e32 v112, 0x52, v162
	s_nop 0
	v_cndmask_b32_e32 v68, v141, v68, vcc
	v_cmp_gt_u32_e32 vcc, s86, v112
	v_add_u32_e32 v112, 0x51, v162
	s_nop 0
	v_cndmask_b32_e32 v69, v141, v69, vcc
	v_cmp_gt_u32_e32 vcc, s86, v112
	v_add_u32_e32 v112, 0x50, v162
	s_nop 0
	v_cndmask_b32_e32 v70, v141, v70, vcc
	v_cmp_gt_u32_e32 vcc, s86, v112
	v_add_u32_e32 v112, 0x4b, v162
	s_nop 0
	v_cndmask_b32_e32 v71, v141, v71, vcc
	v_cmp_gt_u32_e32 vcc, s86, v112
	v_add_u32_e32 v112, 0x4a, v162
	s_nop 0
	v_cndmask_b32_e32 v72, v141, v72, vcc
	v_cmp_gt_u32_e32 vcc, s86, v112
	v_add_u32_e32 v112, 0x49, v162
	s_nop 0
	v_cndmask_b32_e32 v73, v141, v73, vcc
	v_cmp_gt_u32_e32 vcc, s86, v112
	v_add_u32_e32 v112, 0x48, v162
	s_nop 0
	v_cndmask_b32_e32 v74, v141, v74, vcc
	v_cmp_gt_u32_e32 vcc, s86, v112
	v_add_u32_e32 v112, 0x43, v162
	s_nop 0
	v_cndmask_b32_e32 v75, v141, v75, vcc
	v_cmp_gt_u32_e32 vcc, s86, v112
	v_add_u32_e32 v112, 0x42, v162
	s_nop 0
	v_cndmask_b32_e32 v76, v141, v76, vcc
	v_cmp_gt_u32_e32 vcc, s86, v112
	v_add_u32_e32 v112, 0x41, v162
	s_nop 0
	v_cndmask_b32_e32 v77, v141, v77, vcc
	v_cmp_gt_u32_e32 vcc, s86, v112
	v_add_u32_e32 v112, 64, v162
	s_nop 0
	v_cndmask_b32_e32 v78, v141, v78, vcc
	v_cmp_gt_u32_e32 vcc, s86, v112
	s_nop 1
	v_cndmask_b32_e32 v79, v141, v79, vcc
.Li0_sm:
	ds_read_b64_tr_b16 v[180:181], v158 offset:0
	ds_read_b64_tr_b16 v[182:183], v158 offset:0x800
	ds_read_b64_tr_b16 v[184:185], v158 offset:0x1000
	ds_read_b64_tr_b16 v[186:187], v158 offset:0x1800
	ds_read_b64_tr_b16 v[188:189], v158 offset:0x2000
	ds_read_b64_tr_b16 v[190:191], v158 offset:0x2800
	ds_read_b64_tr_b16 v[192:193], v158 offset:0x3000
	ds_read_b64_tr_b16 v[194:195], v158 offset:0x3800
	s_waitcnt lgkmcnt(0)
	s_waitcnt lgkmcnt(0)
	s_nop 1
	v_mfma_f32_32x32x16_bf16 v[48:63], v[176:179], v[180:183], v[48:63]
	ds_read_b64_tr_b16 v[180:181], v158 offset:0x200
	ds_read_b64_tr_b16 v[182:183], v158 offset:0xa00
	v_mul_f32_e32 v114, 0xbe0293ee, v166
	v_max_f32_e32 v112, v65, v65
	v_max_f32_e32 v113, v64, v64
	v_fmamk_f32 v64, v64, 0x3e0293ee, v114
	v_max_f32_e32 v112, v113, v112
	v_exp_f32_e32 v64, v64
	v_mfma_f32_32x32x16_bf16 v[48:63], v[124:127], v[184:187], v[48:63]
	ds_read_b64_tr_b16 v[184:185], v158 offset:0x1200
	ds_read_b64_tr_b16 v[186:187], v158 offset:0x1a00
	v_fmamk_f32 v65, v65, 0x3e0293ee, v114
	v_max3_f32 v112, v112, v66, v67
	v_exp_f32_e32 v65, v65
	v_fmamk_f32 v66, v66, 0x3e0293ee, v114
	v_exp_f32_e32 v66, v66
	v_fmamk_f32 v67, v67, 0x3e0293ee, v114
	v_mfma_f32_32x32x16_bf16 v[48:63], v[172:175], v[188:191], v[48:63]
	ds_read_b64_tr_b16 v[188:189], v158 offset:0x2200
	ds_read_b64_tr_b16 v[190:191], v158 offset:0x2a00
	v_max3_f32 v112, v112, v68, v69
	v_exp_f32_e32 v67, v67
	v_fmamk_f32 v68, v68, 0x3e0293ee, v114
	v_add_f32_e32 v115, 0, v64
	v_exp_f32_e32 v68, v68
	v_fmamk_f32 v69, v69, 0x3e0293ee, v114
	v_mfma_f32_32x32x16_bf16 v[48:63], v[168:171], v[192:195], v[48:63]
	ds_read_b64_tr_b16 v[192:193], v158 offset:0x3200
	ds_read_b64_tr_b16 v[194:195], v158 offset:0x3a00
	v_max3_f32 v112, v112, v70, v71
	v_add_f32_e32 v115, v65, v115
	v_exp_f32_e32 v69, v69
	v_fmamk_f32 v70, v70, 0x3e0293ee, v114
	v_add_f32_e32 v115, v66, v115
	v_exp_f32_e32 v70, v70
	s_waitcnt lgkmcnt(0)
	v_mfma_f32_32x32x16_bf16 v[32:47], v[176:179], v[180:183], v[32:47]
	ds_read_b64_tr_b16 v[180:181], v158 offset:0x400
	ds_read_b64_tr_b16 v[182:183], v158 offset:0xc00
	v_fmamk_f32 v71, v71, 0x3e0293ee, v114
	v_max3_f32 v112, v112, v72, v73
	v_add_f32_e32 v115, v67, v115
	v_exp_f32_e32 v71, v71
	v_fmamk_f32 v72, v72, 0x3e0293ee, v114
	v_add_f32_e32 v115, v68, v115
	v_mfma_f32_32x32x16_bf16 v[32:47], v[124:127], v[184:187], v[32:47]
	ds_read_b64_tr_b16 v[184:185], v158 offset:0x1400
	ds_read_b64_tr_b16 v[186:187], v158 offset:0x1c00
	v_exp_f32_e32 v72, v72
	v_fmamk_f32 v73, v73, 0x3e0293ee, v114
	v_max3_f32 v112, v112, v74, v75
	v_add_f32_e32 v115, v69, v115
	v_exp_f32_e32 v73, v73
	v_fmamk_f32 v74, v74, 0x3e0293ee, v114
	v_mfma_f32_32x32x16_bf16 v[32:47], v[172:175], v[188:191], v[32:47]
	ds_read_b64_tr_b16 v[188:189], v158 offset:0x2400
	ds_read_b64_tr_b16 v[190:191], v158 offset:0x2c00
	v_add_f32_e32 v115, v70, v115
	v_exp_f32_e32 v74, v74
	v_fmamk_f32 v75, v75, 0x3e0293ee, v114
	v_max3_f32 v112, v112, v76, v77
	v_add_f32_e32 v115, v71, v115
	v_exp_f32_e32 v75, v75
	v_mfma_f32_32x32x16_bf16 v[32:47], v[168:171], v[192:195], v[32:47]
	ds_read_b64_tr_b16 v[192:193], v158 offset:0x3400
	ds_read_b64_tr_b16 v[194:195], v158 offset:0x3c00
	v_fmamk_f32 v76, v76, 0x3e0293ee, v114
	v_add_f32_e32 v115, v72, v115
	v_exp_f32_e32 v76, v76
	v_fmamk_f32 v77, v77, 0x3e0293ee, v114
	v_max3_f32 v112, v112, v78, v79
	v_add_f32_e32 v115, v73, v115
	s_waitcnt lgkmcnt(0)
	v_mfma_f32_32x32x16_bf16 v[16:31], v[176:179], v[180:183], v[16:31]
	ds_read_b64_tr_b16 v[180:181], v158 offset:0x600
	ds_read_b64_tr_b16 v[182:183], v158 offset:0xe00
	v_exp_f32_e32 v77, v77
	v_fmamk_f32 v78, v78, 0x3e0293ee, v114
	v_add_f32_e32 v115, v74, v115
	v_exp_f32_e32 v78, v78
	v_fmac_f32_e32 v114, 0x3e0293ee, v79
	v_add_f32_e32 v115, v75, v115
	v_mfma_f32_32x32x16_bf16 v[16:31], v[124:127], v[184:187], v[16:31]
	ds_read_b64_tr_b16 v[184:185], v158 offset:0x1600
	ds_read_b64_tr_b16 v[186:187], v158 offset:0x1e00
	v_exp_f32_e32 v79, v114
	v_add_f32_e32 v114, v76, v115
	v_mov_b32_e32 v113, v112
	v_add_f32_e32 v114, v77, v114
	s_nop 0
	v_permlane32_swap_b32_e32 v112, v113
	v_add_f32_e32 v114, v78, v114
	v_mfma_f32_32x32x16_bf16 v[16:31], v[172:175], v[188:191], v[16:31]
	ds_read_b64_tr_b16 v[188:189], v158 offset:0x2600
	ds_read_b64_tr_b16 v[190:191], v158 offset:0x2e00
	v_add_f32_e32 v120, v79, v114
	v_max_f32_e32 v113, v113, v113
	v_max_f32_e32 v112, v112, v112
	v_max_f32_e32 v164, v112, v113
	v_mov_b32_e32 v121, v120
	v_cvt_pk_bf16_f32 v112, v64, v65
	v_mfma_f32_32x32x16_bf16 v[16:31], v[168:171], v[192:195], v[16:31]
	ds_read_b64_tr_b16 v[192:193], v158 offset:0x3600
	ds_read_b64_tr_b16 v[194:195], v158 offset:0x3e00
	v_cvt_pk_bf16_f32 v113, v66, v67
	v_cvt_pk_bf16_f32 v114, v68, v69
	v_cvt_pk_bf16_f32 v115, v70, v71
	v_cvt_pk_bf16_f32 v116, v72, v73
	v_cvt_pk_bf16_f32 v117, v74, v75
	v_cvt_pk_bf16_f32 v118, v76, v77
	s_waitcnt lgkmcnt(0)
	v_mfma_f32_32x32x16_bf16 v[0:15], v[176:179], v[180:183], v[0:15]
	v_cvt_pk_bf16_f32 v119, v78, v79
	s_nop 1
	v_permlane32_swap_b32_e32 v120, v121
	v_permlane32_swap_b32_e32 v112, v114
	v_permlane32_swap_b32_e32 v113, v115
	v_permlane32_swap_b32_e32 v116, v118
	v_permlane32_swap_b32_e32 v117, v119
	v_mfma_f32_32x32x16_bf16 v[0:15], v[124:127], v[184:187], v[0:15]
	ds_write_b128 v157, v[112:115] offset:4096
	ds_write_b128 v157, v[116:119] offset:5120
	v_add_f32_e32 v120, v120, v121
	v_add_f32_e32 v155, v155, v120
	v_mfma_f32_32x32x16_bf16 v[0:15], v[172:175], v[188:191], v[0:15]
	v_mfma_f32_32x32x16_bf16 v[0:15], v[168:171], v[192:195], v[0:15]
	s_and_saveexec_b64 s[52:53], s[4:5]
	ds_write_b32 v160, v164 offset:8448
	s_or_b64 exec, exec, s[52:53]
	s_waitcnt vmcnt(0)
	s_waitcnt vmcnt(0) lgkmcnt(0)
	s_barrier
	s_branch .LBB0_748

.Li1_entry:
	s_waitcnt lgkmcnt(0)
	v_max_f32_e32 v72, v128, v128
	v_max_f32_e32 v73, v164, v164
	v_max_f32_e32 v72, v73, v72
	v_sub_f32_e32 v73, v72, v166
	v_mul_f32_e32 v73, 0x3db504f3, v73
	v_cmp_ge_f32_e32 vcc, s88, v73
	s_cmp_eq_u64 vcc, exec
	s_cbranch_scc0 .LBB0_751
	ds_read_b128 v[64:67], v148
	ds_read_b128 v[180:183], v150
	s_waitcnt lgkmcnt(0)
	v_mfma_f32_32x32x16_bf16 v[64:79], v[64:67], v[80:83], 0
	v_mfma_f32_32x32x16_bf16 v[64:79], v[180:183], v[84:87], v[64:79]
	ds_read_b128 v[180:183], v152
	s_waitcnt lgkmcnt(0)
	v_mfma_f32_32x32x16_bf16 v[64:79], v[180:183], v[88:91], v[64:79]
	ds_read_b128 v[180:183], v154
	s_waitcnt lgkmcnt(0)
	v_mfma_f32_32x32x16_bf16 v[64:79], v[180:183], v[92:95], v[64:79]
	ds_read_b128 v[180:183], v148 offset:128
	s_waitcnt lgkmcnt(0)
	v_mfma_f32_32x32x16_bf16 v[64:79], v[180:183], v[96:99], v[64:79]
	ds_read_b128 v[180:183], v150 offset:128
	s_waitcnt lgkmcnt(0)
	v_mfma_f32_32x32x16_bf16 v[64:79], v[180:183], v[100:103], v[64:79]
	ds_read_b128 v[180:183], v152 offset:128
	s_waitcnt lgkmcnt(0)
	v_mfma_f32_32x32x16_bf16 v[64:79], v[180:183], v[104:107], v[64:79]
	ds_read_b128 v[180:183], v154 offset:128
	s_waitcnt lgkmcnt(0)
	v_mfma_f32_32x32x16_bf16 v[64:79], v[180:183], v[108:111], v[64:79]
	v_cndmask_b32_e64 v173, v113, v121, s[2:3]
	v_cndmask_b32_e64 v172, v112, v120, s[2:3]
	v_cndmask_b32_e64 v177, v121, v113, s[2:3]
	v_cndmask_b32_e64 v176, v120, v112, s[2:3]
	v_cndmask_b32_e64 v171, v127, v119, s[2:3]
	v_cndmask_b32_e64 v170, v126, v118, s[2:3]
	v_cndmask_b32_e64 v169, v125, v117, s[2:3]
	v_cndmask_b32_e64 v168, v124, v116, s[2:3]
	v_cndmask_b32_e64 v175, v115, v123, s[2:3]
	v_cndmask_b32_e64 v174, v114, v122, s[2:3]
	v_cndmask_b32_e64 v127, v119, v127, s[2:3]
	v_cndmask_b32_e64 v126, v118, v126, s[2:3]
	v_cndmask_b32_e64 v125, v117, v125, s[2:3]
	v_cndmask_b32_e64 v124, v116, v124, s[2:3]
	v_cndmask_b32_e64 v179, v123, v115, s[2:3]
	v_cndmask_b32_e64 v178, v122, v114, s[2:3]
	v_mov_b32_e32 v165, v166
	s_cmp_le_i32 s83, s25
	s_cbranch_scc1 .Li1_sm
	v_add_u32_e32 v112, 27, v162
	v_cmp_gt_u32_e32 vcc, s86, v112
	v_add_u32_e32 v112, s83, v163
	v_subrev_u32_e32 v112, 31, v112
	v_cndmask_b32_e32 v64, v141, v64, vcc
	v_cmp_lt_u32_e32 vcc, s87, v112
	v_add_u32_e32 v112, 25, v162
	s_nop 0
	v_cndmask_b32_e32 v65, v141, v65, vcc
	v_cmp_gt_u32_e32 vcc, s86, v112
	v_add_u32_e32 v112, 24, v162
	s_nop 0
	v_cndmask_b32_e32 v66, v141, v66, vcc
	v_cmp_gt_u32_e32 vcc, s86, v112
	v_add_u32_e32 v112, 19, v162
	s_nop 0
	v_cndmask_b32_e32 v67, v141, v67, vcc
	v_cmp_gt_u32_e32 vcc, s86, v112
	v_add_u32_e32 v112, 18, v162
	s_nop 0
	v_cndmask_b32_e32 v68, v141, v68, vcc
	v_cmp_gt_u32_e32 vcc, s86, v112
	v_add_u32_e32 v112, 17, v162
	s_nop 0
	v_cndmask_b32_e32 v69, v141, v69, vcc
	v_cmp_gt_u32_e32 vcc, s86, v112
	v_add_u32_e32 v112, 16, v162
	s_nop 0
	v_cndmask_b32_e32 v70, v141, v70, vcc
	v_cmp_gt_u32_e32 vcc, s86, v112
	v_add_u32_e32 v112, 11, v162
	s_nop 0
	v_cndmask_b32_e32 v71, v141, v71, vcc
	v_cmp_gt_u32_e32 vcc, s86, v112
	v_add_u32_e32 v112, 10, v162
	s_nop 0
	v_cndmask_b32_e32 v72, v141, v72, vcc
	v_cmp_gt_u32_e32 vcc, s86, v112
	v_add_u32_e32 v112, 9, v162
	s_nop 0
	v_cndmask_b32_e32 v73, v141, v73, vcc
	v_cmp_gt_u32_e32 vcc, s86, v112
	v_add_u32_e32 v112, 8, v162
	s_nop 0
	v_cndmask_b32_e32 v74, v141, v74, vcc
	v_cmp_gt_u32_e32 vcc, s86, v112
	v_add_u32_e32 v112, 3, v162
	s_nop 0
	v_cndmask_b32_e32 v75, v141, v75, vcc
	v_cmp_gt_u32_e32 vcc, s86, v112
	v_add_u32_e32 v112, 2, v162
	s_nop 0
	v_cndmask_b32_e32 v76, v141, v76, vcc
	v_cmp_gt_u32_e32 vcc, s86, v112
	v_add_u32_e32 v112, 1, v162
	s_nop 0
	v_cndmask_b32_e32 v77, v141, v77, vcc
	v_cmp_gt_u32_e32 vcc, s86, v112
	s_nop 1
	v_cndmask_b32_e32 v78, v141, v78, vcc
	v_cmp_gt_u32_e32 vcc, s86, v162
	s_nop 1
	v_cndmask_b32_e32 v79, v141, v79, vcc
.Li1_sm:
	ds_read_b64_tr_b16 v[180:181], v158 offset:0x8000
	ds_read_b64_tr_b16 v[182:183], v158 offset:0x8800
	ds_read_b64_tr_b16 v[184:185], v158 offset:0x9000
	ds_read_b64_tr_b16 v[186:187], v158 offset:0x9800
	ds_read_b64_tr_b16 v[188:189], v158 offset:0xa000
	ds_read_b64_tr_b16 v[190:191], v158 offset:0xa800
	ds_read_b64_tr_b16 v[192:193], v158 offset:0xb000
	ds_read_b64_tr_b16 v[194:195], v158 offset:0xb800
	s_waitcnt lgkmcnt(0)
	s_waitcnt lgkmcnt(0)
	s_nop 1
	v_mfma_f32_32x32x16_bf16 v[48:63], v[176:179], v[180:183], v[48:63]
	ds_read_b64_tr_b16 v[180:181], v158 offset:0x8200
	ds_read_b64_tr_b16 v[182:183], v158 offset:0x8a00
	v_mul_f32_e32 v114, 0xbe0293ee, v165
	v_max_f32_e32 v112, v65, v65
	v_max_f32_e32 v113, v64, v64
	v_fmamk_f32 v64, v64, 0x3e0293ee, v114
	v_max_f32_e32 v112, v113, v112
	v_exp_f32_e32 v64, v64
	v_mfma_f32_32x32x16_bf16 v[48:63], v[168:171], v[184:187], v[48:63]
	ds_read_b64_tr_b16 v[184:185], v158 offset:0x9200
	ds_read_b64_tr_b16 v[186:187], v158 offset:0x9a00
	v_fmamk_f32 v65, v65, 0x3e0293ee, v114
	v_max3_f32 v112, v112, v66, v67
	v_exp_f32_e32 v65, v65
	v_fmamk_f32 v66, v66, 0x3e0293ee, v114
	v_exp_f32_e32 v66, v66
	v_fmamk_f32 v67, v67, 0x3e0293ee, v114
	v_mfma_f32_32x32x16_bf16 v[48:63], v[172:175], v[188:191], v[48:63]
	ds_read_b64_tr_b16 v[188:189], v158 offset:0xa200
	ds_read_b64_tr_b16 v[190:191], v158 offset:0xaa00
	v_max3_f32 v112, v112, v68, v69
	v_exp_f32_e32 v67, v67
	v_fmamk_f32 v68, v68, 0x3e0293ee, v114
	v_add_f32_e32 v115, 0, v64
	v_exp_f32_e32 v68, v68
	v_fmamk_f32 v69, v69, 0x3e0293ee, v114
	v_mfma_f32_32x32x16_bf16 v[48:63], v[124:127], v[192:195], v[48:63]
	ds_read_b64_tr_b16 v[192:193], v158 offset:0xb200
	ds_read_b64_tr_b16 v[194:195], v158 offset:0xba00
	v_max3_f32 v112, v112, v70, v71
	v_add_f32_e32 v115, v65, v115
	v_exp_f32_e32 v69, v69
	v_fmamk_f32 v70, v70, 0x3e0293ee, v114
	v_add_f32_e32 v115, v66, v115
	v_exp_f32_e32 v70, v70
	s_waitcnt lgkmcnt(0)
	v_mfma_f32_32x32x16_bf16 v[32:47], v[176:179], v[180:183], v[32:47]
	ds_read_b64_tr_b16 v[180:181], v158 offset:0x8400
	ds_read_b64_tr_b16 v[182:183], v158 offset:0x8c00
	v_fmamk_f32 v71, v71, 0x3e0293ee, v114
	v_max3_f32 v112, v112, v72, v73
	v_add_f32_e32 v115, v67, v115
	v_exp_f32_e32 v71, v71
	v_fmamk_f32 v72, v72, 0x3e0293ee, v114
	v_add_f32_e32 v115, v68, v115
	v_mfma_f32_32x32x16_bf16 v[32:47], v[168:171], v[184:187], v[32:47]
	ds_read_b64_tr_b16 v[184:185], v158 offset:0x9400
	ds_read_b64_tr_b16 v[186:187], v158 offset:0x9c00
	v_exp_f32_e32 v72, v72
	v_fmamk_f32 v73, v73, 0x3e0293ee, v114
	v_max3_f32 v112, v112, v74, v75
	v_add_f32_e32 v115, v69, v115
	v_exp_f32_e32 v73, v73
	v_fmamk_f32 v74, v74, 0x3e0293ee, v114
	v_mfma_f32_32x32x16_bf16 v[32:47], v[172:175], v[188:191], v[32:47]
	ds_read_b64_tr_b16 v[188:189], v158 offset:0xa400
	ds_read_b64_tr_b16 v[190:191], v158 offset:0xac00
	v_add_f32_e32 v115, v70, v115
	v_exp_f32_e32 v74, v74
	v_fmamk_f32 v75, v75, 0x3e0293ee, v114
	v_max3_f32 v112, v112, v76, v77
	v_add_f32_e32 v115, v71, v115
	v_exp_f32_e32 v75, v75
	v_mfma_f32_32x32x16_bf16 v[32:47], v[124:127], v[192:195], v[32:47]
	ds_read_b64_tr_b16 v[192:193], v158 offset:0xb400
	ds_read_b64_tr_b16 v[194:195], v158 offset:0xbc00
	v_fmamk_f32 v76, v76, 0x3e0293ee, v114
	v_add_f32_e32 v115, v72, v115
	v_exp_f32_e32 v76, v76
	v_fmamk_f32 v77, v77, 0x3e0293ee, v114
	v_max3_f32 v112, v112, v78, v79
	v_add_f32_e32 v115, v73, v115
	s_waitcnt lgkmcnt(0)
	v_mfma_f32_32x32x16_bf16 v[16:31], v[176:179], v[180:183], v[16:31]
	ds_read_b64_tr_b16 v[180:181], v158 offset:0x8600
	ds_read_b64_tr_b16 v[182:183], v158 offset:0x8e00
	v_exp_f32_e32 v77, v77
	v_fmamk_f32 v78, v78, 0x3e0293ee, v114
	v_add_f32_e32 v115, v74, v115
	v_exp_f32_e32 v78, v78
	v_fmac_f32_e32 v114, 0x3e0293ee, v79
	v_add_f32_e32 v115, v75, v115
	v_mfma_f32_32x32x16_bf16 v[16:31], v[168:171], v[184:187], v[16:31]
	ds_read_b64_tr_b16 v[184:185], v158 offset:0x9600
	ds_read_b64_tr_b16 v[186:187], v158 offset:0x9e00
	v_exp_f32_e32 v79, v114
	v_add_f32_e32 v114, v76, v115
	v_mov_b32_e32 v113, v112
	v_add_f32_e32 v114, v77, v114
	s_nop 0
	v_permlane32_swap_b32_e32 v112, v113
	v_add_f32_e32 v114, v78, v114
	v_mfma_f32_32x32x16_bf16 v[16:31], v[172:175], v[188:191], v[16:31]
	ds_read_b64_tr_b16 v[188:189], v158 offset:0xa600
	ds_read_b64_tr_b16 v[190:191], v158 offset:0xae00
	v_add_f32_e32 v120, v79, v114
	v_max_f32_e32 v113, v113, v113
	v_max_f32_e32 v112, v112, v112
	v_max_f32_e32 v164, v112, v113
	v_mov_b32_e32 v121, v120
	v_cvt_pk_bf16_f32 v112, v64, v65
	v_mfma_f32_32x32x16_bf16 v[16:31], v[124:127], v[192:195], v[16:31]
	ds_read_b64_tr_b16 v[192:193], v158 offset:0xb600
	ds_read_b64_tr_b16 v[194:195], v158 offset:0xbe00
	v_cvt_pk_bf16_f32 v113, v66, v67
	v_cvt_pk_bf16_f32 v114, v68, v69
	v_cvt_pk_bf16_f32 v115, v70, v71
	v_cvt_pk_bf16_f32 v116, v72, v73
	v_cvt_pk_bf16_f32 v117, v74, v75
	v_cvt_pk_bf16_f32 v118, v76, v77
	s_waitcnt lgkmcnt(0)
	v_mfma_f32_32x32x16_bf16 v[0:15], v[176:179], v[180:183], v[0:15]
	v_cvt_pk_bf16_f32 v119, v78, v79
	s_nop 1
	v_permlane32_swap_b32_e32 v120, v121
	v_permlane32_swap_b32_e32 v112, v114
	v_permlane32_swap_b32_e32 v113, v115
	v_permlane32_swap_b32_e32 v116, v118
	v_permlane32_swap_b32_e32 v117, v119
	v_mfma_f32_32x32x16_bf16 v[0:15], v[168:171], v[184:187], v[0:15]
	ds_write_b128 v157, v[112:115]
	ds_write_b128 v157, v[116:119] offset:1024
	v_add_f32_e32 v120, v120, v121
	v_add_f32_e32 v155, v155, v120
	v_mfma_f32_32x32x16_bf16 v[0:15], v[172:175], v[188:191], v[0:15]
	v_mfma_f32_32x32x16_bf16 v[0:15], v[124:127], v[192:195], v[0:15]
	s_and_saveexec_b64 s[54:55], s[4:5]
	ds_write_b32 v160, v164 offset:8192
	s_or_b64 exec, exec, s[54:55]
	s_waitcnt vmcnt(0)
	s_waitcnt vmcnt(0) lgkmcnt(0)
	s_barrier
	s_branch .LBB0_733
